# bundle plus attention bias loads issued before the per-tile barrier
# baseline (speedup 1.0000x reference)
.Lat_tile_top:
	s_cmp_lt_u32 s71, s78
	s_cbranch_scc0 .Lat_top_nobias
	s_add_i32 s27, s32, s71
	s_sub_i32 s70, s27, s15
	s_cmp_lt_u32 s70, s2
	s_cbranch_scc0 .Lat_top_nobias
	v_add_u32_e32 v247, 8, v188
	v_med3_i32 v247, v247, 0, s22
	v_lshlrev_b32_e32 v247, 2, v247
	global_load_dword v213, v247, s[0:1]
	v_add_u32_e32 v248, 9, v188
	v_med3_i32 v248, v248, 0, s22
	v_lshlrev_b32_e32 v248, 2, v248
	global_load_dword v214, v248, s[0:1]
	v_add_u32_e32 v247, 10, v188
	v_med3_i32 v247, v247, 0, s22
	v_lshlrev_b32_e32 v247, 2, v247
	global_load_dword v215, v247, s[0:1]
	v_add_u32_e32 v248, 11, v188
	v_med3_i32 v248, v248, 0, s22
	v_lshlrev_b32_e32 v248, 2, v248
	global_load_dword v216, v248, s[0:1]
	v_add_u32_e32 v247, 12, v188
	v_med3_i32 v247, v247, 0, s22
	v_lshlrev_b32_e32 v247, 2, v247
	global_load_dword v217, v247, s[0:1]
	v_add_u32_e32 v248, 13, v188
	v_med3_i32 v248, v248, 0, s22
	v_lshlrev_b32_e32 v248, 2, v248
	global_load_dword v218, v248, s[0:1]
	v_add_u32_e32 v247, 14, v188
	v_med3_i32 v247, v247, 0, s22
	v_lshlrev_b32_e32 v247, 2, v247
	global_load_dword v219, v247, s[0:1]
	v_add_u32_e32 v248, 15, v188
	v_med3_i32 v248, v248, 0, s22
	v_lshlrev_b32_e32 v248, 2, v248
	global_load_dword v220, v248, s[0:1]
	v_subrev_u32_e32 v247, 23, v188
	v_med3_i32 v247, v247, 0, s22
	v_lshlrev_b32_e32 v247, 2, v247
	global_load_dword v221, v247, s[0:1]
	v_subrev_u32_e32 v248, 22, v188
	v_med3_i32 v248, v248, 0, s22
	v_lshlrev_b32_e32 v248, 2, v248
	global_load_dword v222, v248, s[0:1]
	v_subrev_u32_e32 v247, 21, v188
	v_med3_i32 v247, v247, 0, s22
	v_lshlrev_b32_e32 v247, 2, v247
	global_load_dword v223, v247, s[0:1]
	v_subrev_u32_e32 v248, 20, v188
	v_med3_i32 v248, v248, 0, s22
	v_lshlrev_b32_e32 v248, 2, v248
	global_load_dword v224, v248, s[0:1]
	v_subrev_u32_e32 v247, 19, v188
	v_med3_i32 v247, v247, 0, s22
	v_lshlrev_b32_e32 v247, 2, v247
	global_load_dword v225, v247, s[0:1]
	v_subrev_u32_e32 v248, 18, v188
	v_med3_i32 v248, v248, 0, s22
	v_lshlrev_b32_e32 v248, 2, v248
	global_load_dword v226, v248, s[0:1]
	v_subrev_u32_e32 v247, 17, v188
	v_med3_i32 v247, v247, 0, s22
	v_lshlrev_b32_e32 v247, 2, v247
	global_load_dword v227, v247, s[0:1]
	v_subrev_u32_e32 v248, 16, v188
	v_med3_i32 v248, v248, 0, s22
	v_lshlrev_b32_e32 v248, 2, v248
	global_load_dword v228, v248, s[0:1]
	s_waitcnt vmcnt(20)
	s_branch .Lat_wdone

.Lat_wdone:
	s_barrier
	s_cmp_lt_u32 s71, s78
	s_cbranch_scc0 .Lat_ctx_tile
	s_add_i32 s27, s32, s71
	s_sub_i32 s70, s27, s15
	s_cmp_lt_u32 s70, s2
	s_cselect_b32 s100, 1, 0
	s_cbranch_scc0 .Lat_loc_dma
	v_add_u32_e32 v242, s99, v255
	v_xor_b32_e32 v243, 64, v255
	v_xor_b32_e32 v244, 0x80, v255
	v_xor_b32_e32 v245, 0xc0, v255
	v_add_u32_e32 v243, s99, v243
	v_add_u32_e32 v244, s99, v244
	v_add_u32_e32 v245, s99, v245
	v_add_u32_e32 v246, s99, v191
	ds_read_b128 v[142:145], v242
	ds_read_b128 v[130:133], v243
	ds_read_b128 v[134:137], v244
	ds_read_b128 v[138:141], v245
	ds_read_b128 v[158:161], v242 offset:1024
	ds_read_b128 v[150:153], v243 offset:1024
	ds_read_b128 v[154:157], v244 offset:1024
	ds_read_b128 v[146:149], v245 offset:1024
	ds_read_b128 v[126:129], v246
	ds_read_b128 v[122:125], v246 offset:2048
	ds_read_b128 v[118:121], v246 offset:4096
	ds_read_b128 v[114:117], v246 offset:6144
	ds_read_b128 v[110:113], v246 offset:8192
	ds_read_b128 v[106:109], v246 offset:10240
	ds_read_b128 v[102:105], v246 offset:12288
	ds_read_b128 v[98:101], v246 offset:14336
	s_add_i32 s9, s71, 2
	s_sub_i32 s27, s9, s78
	s_lshr_b32 s42, s23, 9
	s_lshl_b32 s101, s42, 2
	s_add_i32 s27, s27, s101
	s_add_i32 s27, s27, 0x100
	s_lshl_b32 s42, s42, 5
	s_add_i32 s42, s42, s32
	s_add_i32 s42, s42, s9
	s_cmp_lt_u32 s9, s78
	s_cselect_b32 s27, s42, s27
	s_lshl_b32 s27, s27, 6
	s_mul_i32 s42, s27, s37
	s_add_u32 s10, s50, s42
	s_addc_u32 s11, s51, 0
	s_lshl_b32 s101, s13, 1
	s_add_i32 s101, s101, 0x2800
	s_add_u32 s10, s10, s101
	s_addc_u32 s11, s11, 0
	s_lshl_b32 s8, s12, 10
	s_add_i32 s8, s8, s98
	s_mov_b32 m0, s8
	s_add_i32 s8, s8, 0x2000
	global_load_lds_dwordx4 v229, s[10:11]
	s_mov_b32 m0, s8
	s_add_u32 s10, s10, 0xd0000
	s_addc_u32 s11, s11, 0
	global_load_lds_dwordx4 v229, s[10:11]
	v_readlane_b32 s10, v252, 55
	v_readlane_b32 s11, v252, 56
	s_mul_i32 s42, s13, 0x9000
	s_lshl_b32 s101, s27, 1
	s_add_i32 s42, s42, s101
	s_add_i32 s8, s8, 0x2000
	s_add_u32 s10, s10, s42
	s_addc_u32 s11, s11, 0
	s_mov_b32 m0, s8
	s_add_i32 s8, s8, 0x2000
	global_load_lds_dwordx4 v254, s[10:11]
	s_mov_b32 m0, s8
	s_add_u32 s10, s10, 0x240000
	s_addc_u32 s11, s11, 0
	global_load_lds_dwordx4 v254, s[10:11]
	s_add_i32 s98, s98, 0x8000
	s_cmp_eq_u32 s98, 0x18000
	s_cselect_b32 s98, 0x0, s98
	s_mov_b32 s100, 2
	s_branch .Lat_body
